# s5 pass A: B*u products on f32 matrix cores (v_mfma_f32_32x32x2_f32, exact f32), step loop keeps only the state rotation
# speedup vs baseline: 1.0022x; 1.0022x over previous
.LBB0_279:
	v_and_b32_e32 v41, 31, v226
	v_and_b32_e32 v126, 32, v226
	v_lshlrev_b32_e32 v41, 6, v41
	v_add3_u32 v41, v41, v126, v35
	ds_read_b128 v[110:113], v41
	ds_read_b128 v[114:117], v41 offset:16
	ds_read_b128 v[118:121], v41 offset:2048
	ds_read_b128 v[122:125], v41 offset:2064
	v_sub_f32_e32 v127, 0, v106
	s_nop 1
	v_permlane32_swap_b32_e32 v108, v22
	v_permlane32_swap_b32_e32 v109, v23
	v_permlane32_swap_b32_e32 v28, v12
	v_permlane32_swap_b32_e32 v29, v13
	v_permlane32_swap_b32_e32 v24, v8
	v_permlane32_swap_b32_e32 v25, v9
	v_permlane32_swap_b32_e32 v26, v10
	v_permlane32_swap_b32_e32 v27, v11
	v_permlane32_swap_b32_e32 v30, v14
	v_permlane32_swap_b32_e32 v31, v15
	v_permlane32_swap_b32_e32 v20, v4
	v_permlane32_swap_b32_e32 v21, v5
	v_permlane32_swap_b32_e32 v16, v0
	v_permlane32_swap_b32_e32 v17, v1
	v_permlane32_swap_b32_e32 v18, v2
	v_permlane32_swap_b32_e32 v19, v3
	s_waitcnt lgkmcnt(2)
	s_nop 1
	v_mfma_f32_32x32x2_f32 v[176:191], v110, v108, 0
	v_mfma_f32_32x32x2_f32 v[192:207], v110, v22, 0
	v_mfma_f32_32x32x2_f32 v[208:223], v110, v109, 0
	v_mfma_f32_32x32x2_f32 v[144:159], v110, v23, 0
	v_mfma_f32_32x32x2_f32 v[176:191], v111, v28, v[176:191]
	v_mfma_f32_32x32x2_f32 v[192:207], v111, v12, v[192:207]
	v_mfma_f32_32x32x2_f32 v[208:223], v111, v29, v[208:223]
	v_mfma_f32_32x32x2_f32 v[144:159], v111, v13, v[144:159]
	v_mfma_f32_32x32x2_f32 v[176:191], v112, v24, v[176:191]
	v_mfma_f32_32x32x2_f32 v[192:207], v112, v8, v[192:207]
	v_mfma_f32_32x32x2_f32 v[208:223], v112, v25, v[208:223]
	v_mfma_f32_32x32x2_f32 v[144:159], v112, v9, v[144:159]
	v_mfma_f32_32x32x2_f32 v[176:191], v113, v26, v[176:191]
	v_mfma_f32_32x32x2_f32 v[192:207], v113, v10, v[192:207]
	v_mfma_f32_32x32x2_f32 v[208:223], v113, v27, v[208:223]
	v_mfma_f32_32x32x2_f32 v[144:159], v113, v11, v[144:159]
	v_mfma_f32_32x32x2_f32 v[176:191], v114, v30, v[176:191]
	v_mfma_f32_32x32x2_f32 v[192:207], v114, v14, v[192:207]
	v_mfma_f32_32x32x2_f32 v[208:223], v114, v31, v[208:223]
	v_mfma_f32_32x32x2_f32 v[144:159], v114, v15, v[144:159]
	v_mfma_f32_32x32x2_f32 v[176:191], v115, v20, v[176:191]
	v_mfma_f32_32x32x2_f32 v[192:207], v115, v4, v[192:207]
	v_mfma_f32_32x32x2_f32 v[208:223], v115, v21, v[208:223]
	v_mfma_f32_32x32x2_f32 v[144:159], v115, v5, v[144:159]
	v_mfma_f32_32x32x2_f32 v[176:191], v116, v16, v[176:191]
	v_mfma_f32_32x32x2_f32 v[192:207], v116, v0, v[192:207]
	v_mfma_f32_32x32x2_f32 v[208:223], v116, v17, v[208:223]
	v_mfma_f32_32x32x2_f32 v[144:159], v116, v1, v[144:159]
	v_mfma_f32_32x32x2_f32 v[176:191], v117, v18, v[176:191]
	v_mfma_f32_32x32x2_f32 v[192:207], v117, v2, v[192:207]
	v_mfma_f32_32x32x2_f32 v[208:223], v117, v19, v[208:223]
	v_mfma_f32_32x32x2_f32 v[144:159], v117, v3, v[144:159]
	s_nop 7
	s_nop 7
	s_nop 3
	v_permlane32_swap_b32_e32 v176, v192
	v_permlane32_swap_b32_e32 v208, v144
	v_permlane32_swap_b32_e32 v177, v193
	v_permlane32_swap_b32_e32 v209, v145
	v_permlane32_swap_b32_e32 v178, v194
	v_permlane32_swap_b32_e32 v210, v146
	v_permlane32_swap_b32_e32 v179, v195
	v_permlane32_swap_b32_e32 v211, v147
	v_permlane32_swap_b32_e32 v180, v196
	v_permlane32_swap_b32_e32 v212, v148
	v_permlane32_swap_b32_e32 v181, v197
	v_permlane32_swap_b32_e32 v213, v149
	v_permlane32_swap_b32_e32 v182, v198
	v_permlane32_swap_b32_e32 v214, v150
	v_permlane32_swap_b32_e32 v183, v199
	v_permlane32_swap_b32_e32 v215, v151
	v_permlane32_swap_b32_e32 v184, v200
	v_permlane32_swap_b32_e32 v216, v152
	v_permlane32_swap_b32_e32 v185, v201
	v_permlane32_swap_b32_e32 v217, v153
	v_permlane32_swap_b32_e32 v186, v202
	v_permlane32_swap_b32_e32 v218, v154
	v_permlane32_swap_b32_e32 v187, v203
	v_permlane32_swap_b32_e32 v219, v155
	v_permlane32_swap_b32_e32 v188, v204
	v_permlane32_swap_b32_e32 v220, v156
	v_permlane32_swap_b32_e32 v189, v205
	v_permlane32_swap_b32_e32 v221, v157
	v_permlane32_swap_b32_e32 v190, v206
	v_permlane32_swap_b32_e32 v222, v158
	v_permlane32_swap_b32_e32 v191, v207
	v_permlane32_swap_b32_e32 v223, v159
	s_nop 1
	v_fmac_f32_e32 v177, v104, v176
	v_fmac_f32_e32 v209, v104, v208
	v_fmac_f32_e32 v177, v127, v208
	v_fmac_f32_e32 v209, v106, v176
	v_fmac_f32_e32 v178, v104, v177
	v_fmac_f32_e32 v210, v104, v209
	v_fmac_f32_e32 v178, v127, v209
	v_fmac_f32_e32 v210, v106, v177
	v_fmac_f32_e32 v179, v104, v178
	v_fmac_f32_e32 v211, v104, v210
	v_fmac_f32_e32 v179, v127, v210
	v_fmac_f32_e32 v211, v106, v178
	v_fmac_f32_e32 v192, v104, v179
	v_fmac_f32_e32 v144, v104, v211
	v_fmac_f32_e32 v192, v127, v211
	v_fmac_f32_e32 v144, v106, v179
	v_fmac_f32_e32 v193, v104, v192
	v_fmac_f32_e32 v145, v104, v144
	v_fmac_f32_e32 v193, v127, v144
	v_fmac_f32_e32 v145, v106, v192
	v_fmac_f32_e32 v194, v104, v193
	v_fmac_f32_e32 v146, v104, v145
	v_fmac_f32_e32 v194, v127, v145
	v_fmac_f32_e32 v146, v106, v193
	v_fmac_f32_e32 v195, v104, v194
	v_fmac_f32_e32 v147, v104, v146
	v_fmac_f32_e32 v195, v127, v146
	v_fmac_f32_e32 v147, v106, v194
	v_fmac_f32_e32 v180, v104, v195
	v_fmac_f32_e32 v212, v104, v147
	v_fmac_f32_e32 v180, v127, v147
	v_fmac_f32_e32 v212, v106, v195
	v_fmac_f32_e32 v181, v104, v180
	v_fmac_f32_e32 v213, v104, v212
	v_fmac_f32_e32 v181, v127, v212
	v_fmac_f32_e32 v213, v106, v180
	v_fmac_f32_e32 v182, v104, v181
	v_fmac_f32_e32 v214, v104, v213
	v_fmac_f32_e32 v182, v127, v213
	v_fmac_f32_e32 v214, v106, v181
	v_fmac_f32_e32 v183, v104, v182
	v_fmac_f32_e32 v215, v104, v214
	v_fmac_f32_e32 v183, v127, v214
	v_fmac_f32_e32 v215, v106, v182
	v_fmac_f32_e32 v196, v104, v183
	v_fmac_f32_e32 v148, v104, v215
	v_fmac_f32_e32 v196, v127, v215
	v_fmac_f32_e32 v148, v106, v183
	v_fmac_f32_e32 v197, v104, v196
	v_fmac_f32_e32 v149, v104, v148
	v_fmac_f32_e32 v197, v127, v148
	v_fmac_f32_e32 v149, v106, v196
	v_fmac_f32_e32 v198, v104, v197
	v_fmac_f32_e32 v150, v104, v149
	v_fmac_f32_e32 v198, v127, v149
	v_fmac_f32_e32 v150, v106, v197
	v_fmac_f32_e32 v199, v104, v198
	v_fmac_f32_e32 v151, v104, v150
	v_fmac_f32_e32 v199, v127, v150
	v_fmac_f32_e32 v151, v106, v198
	v_fmac_f32_e32 v184, v104, v199
	v_fmac_f32_e32 v216, v104, v151
	v_fmac_f32_e32 v184, v127, v151
	v_fmac_f32_e32 v216, v106, v199
	v_fmac_f32_e32 v185, v104, v184
	v_fmac_f32_e32 v217, v104, v216
	v_fmac_f32_e32 v185, v127, v216
	v_fmac_f32_e32 v217, v106, v184
	v_fmac_f32_e32 v186, v104, v185
	v_fmac_f32_e32 v218, v104, v217
	v_fmac_f32_e32 v186, v127, v217
	v_fmac_f32_e32 v218, v106, v185
	v_fmac_f32_e32 v187, v104, v186
	v_fmac_f32_e32 v219, v104, v218
	v_fmac_f32_e32 v187, v127, v218
	v_fmac_f32_e32 v219, v106, v186
	v_fmac_f32_e32 v200, v104, v187
	v_fmac_f32_e32 v152, v104, v219
	v_fmac_f32_e32 v200, v127, v219
	v_fmac_f32_e32 v152, v106, v187
	v_fmac_f32_e32 v201, v104, v200
	v_fmac_f32_e32 v153, v104, v152
	v_fmac_f32_e32 v201, v127, v152
	v_fmac_f32_e32 v153, v106, v200
	v_fmac_f32_e32 v202, v104, v201
	v_fmac_f32_e32 v154, v104, v153
	v_fmac_f32_e32 v202, v127, v153
	v_fmac_f32_e32 v154, v106, v201
	v_fmac_f32_e32 v203, v104, v202
	v_fmac_f32_e32 v155, v104, v154
	v_fmac_f32_e32 v203, v127, v154
	v_fmac_f32_e32 v155, v106, v202
	v_fmac_f32_e32 v188, v104, v203
	v_fmac_f32_e32 v220, v104, v155
	v_fmac_f32_e32 v188, v127, v155
	v_fmac_f32_e32 v220, v106, v203
	v_fmac_f32_e32 v189, v104, v188
	v_fmac_f32_e32 v221, v104, v220
	v_fmac_f32_e32 v189, v127, v220
	v_fmac_f32_e32 v221, v106, v188
	v_fmac_f32_e32 v190, v104, v189
	v_fmac_f32_e32 v222, v104, v221
	v_fmac_f32_e32 v190, v127, v221
	v_fmac_f32_e32 v222, v106, v189
	v_fmac_f32_e32 v191, v104, v190
	v_fmac_f32_e32 v223, v104, v222
	v_fmac_f32_e32 v191, v127, v222
	v_fmac_f32_e32 v223, v106, v190
	v_fmac_f32_e32 v204, v104, v191
	v_fmac_f32_e32 v156, v104, v223
	v_fmac_f32_e32 v204, v127, v223
	v_fmac_f32_e32 v156, v106, v191
	v_fmac_f32_e32 v205, v104, v204
	v_fmac_f32_e32 v157, v104, v156
	v_fmac_f32_e32 v205, v127, v156
	v_fmac_f32_e32 v157, v106, v204
	v_fmac_f32_e32 v206, v104, v205
	v_fmac_f32_e32 v158, v104, v157
	v_fmac_f32_e32 v206, v127, v157
	v_fmac_f32_e32 v158, v106, v205
	v_fmac_f32_e32 v207, v104, v206
	v_fmac_f32_e32 v159, v104, v158
	v_fmac_f32_e32 v207, v127, v158
	v_fmac_f32_e32 v159, v106, v206
	v_mov_b32_e32 v6, v207
	v_mov_b32_e32 v7, v159
	s_waitcnt lgkmcnt(0)
	v_mfma_f32_32x32x2_f32 v[176:191], v118, v108, 0
	v_mfma_f32_32x32x2_f32 v[192:207], v118, v22, 0
	v_mfma_f32_32x32x2_f32 v[208:223], v118, v109, 0
	v_mfma_f32_32x32x2_f32 v[144:159], v118, v23, 0
	v_mfma_f32_32x32x2_f32 v[176:191], v119, v28, v[176:191]
	v_mfma_f32_32x32x2_f32 v[192:207], v119, v12, v[192:207]
	v_mfma_f32_32x32x2_f32 v[208:223], v119, v29, v[208:223]
	v_mfma_f32_32x32x2_f32 v[144:159], v119, v13, v[144:159]
	v_mfma_f32_32x32x2_f32 v[176:191], v120, v24, v[176:191]
	v_mfma_f32_32x32x2_f32 v[192:207], v120, v8, v[192:207]
	v_mfma_f32_32x32x2_f32 v[208:223], v120, v25, v[208:223]
	v_mfma_f32_32x32x2_f32 v[144:159], v120, v9, v[144:159]
	v_mfma_f32_32x32x2_f32 v[176:191], v121, v26, v[176:191]
	v_mfma_f32_32x32x2_f32 v[192:207], v121, v10, v[192:207]
	v_mfma_f32_32x32x2_f32 v[208:223], v121, v27, v[208:223]
	v_mfma_f32_32x32x2_f32 v[144:159], v121, v11, v[144:159]
	v_mfma_f32_32x32x2_f32 v[176:191], v122, v30, v[176:191]
	v_mfma_f32_32x32x2_f32 v[192:207], v122, v14, v[192:207]
	v_mfma_f32_32x32x2_f32 v[208:223], v122, v31, v[208:223]
	v_mfma_f32_32x32x2_f32 v[144:159], v122, v15, v[144:159]
	v_mfma_f32_32x32x2_f32 v[176:191], v123, v20, v[176:191]
	v_mfma_f32_32x32x2_f32 v[192:207], v123, v4, v[192:207]
	v_mfma_f32_32x32x2_f32 v[208:223], v123, v21, v[208:223]
	v_mfma_f32_32x32x2_f32 v[144:159], v123, v5, v[144:159]
	v_mfma_f32_32x32x2_f32 v[176:191], v124, v16, v[176:191]
	v_mfma_f32_32x32x2_f32 v[192:207], v124, v0, v[192:207]
	v_mfma_f32_32x32x2_f32 v[208:223], v124, v17, v[208:223]
	v_mfma_f32_32x32x2_f32 v[144:159], v124, v1, v[144:159]
	v_mfma_f32_32x32x2_f32 v[176:191], v125, v18, v[176:191]
	v_mfma_f32_32x32x2_f32 v[192:207], v125, v2, v[192:207]
	v_mfma_f32_32x32x2_f32 v[208:223], v125, v19, v[208:223]
	v_mfma_f32_32x32x2_f32 v[144:159], v125, v3, v[144:159]
	s_nop 7
	s_nop 7
	s_nop 3
	v_permlane32_swap_b32_e32 v176, v192
	v_permlane32_swap_b32_e32 v208, v144
	v_permlane32_swap_b32_e32 v177, v193
	v_permlane32_swap_b32_e32 v209, v145
	v_permlane32_swap_b32_e32 v178, v194
	v_permlane32_swap_b32_e32 v210, v146
	v_permlane32_swap_b32_e32 v179, v195
	v_permlane32_swap_b32_e32 v211, v147
	v_permlane32_swap_b32_e32 v180, v196
	v_permlane32_swap_b32_e32 v212, v148
	v_permlane32_swap_b32_e32 v181, v197
	v_permlane32_swap_b32_e32 v213, v149
	v_permlane32_swap_b32_e32 v182, v198
	v_permlane32_swap_b32_e32 v214, v150
	v_permlane32_swap_b32_e32 v183, v199
	v_permlane32_swap_b32_e32 v215, v151
	v_permlane32_swap_b32_e32 v184, v200
	v_permlane32_swap_b32_e32 v216, v152
	v_permlane32_swap_b32_e32 v185, v201
	v_permlane32_swap_b32_e32 v217, v153
	v_permlane32_swap_b32_e32 v186, v202
	v_permlane32_swap_b32_e32 v218, v154
	v_permlane32_swap_b32_e32 v187, v203
	v_permlane32_swap_b32_e32 v219, v155
	v_permlane32_swap_b32_e32 v188, v204
	v_permlane32_swap_b32_e32 v220, v156
	v_permlane32_swap_b32_e32 v189, v205
	v_permlane32_swap_b32_e32 v221, v157
	v_permlane32_swap_b32_e32 v190, v206
	v_permlane32_swap_b32_e32 v222, v158
	v_permlane32_swap_b32_e32 v191, v207
	v_permlane32_swap_b32_e32 v223, v159
	s_nop 1
	v_fmac_f32_e32 v176, v104, v6
	v_fmac_f32_e32 v208, v104, v7
	v_fmac_f32_e32 v176, v127, v7
	v_fmac_f32_e32 v208, v106, v6
	v_fmac_f32_e32 v177, v104, v176
	v_fmac_f32_e32 v209, v104, v208
	v_fmac_f32_e32 v177, v127, v208
	v_fmac_f32_e32 v209, v106, v176
	v_fmac_f32_e32 v178, v104, v177
	v_fmac_f32_e32 v210, v104, v209
	v_fmac_f32_e32 v178, v127, v209
	v_fmac_f32_e32 v210, v106, v177
	v_fmac_f32_e32 v179, v104, v178
	v_fmac_f32_e32 v211, v104, v210
	v_fmac_f32_e32 v179, v127, v210
	v_fmac_f32_e32 v211, v106, v178
	v_fmac_f32_e32 v192, v104, v179
	v_fmac_f32_e32 v144, v104, v211
	v_fmac_f32_e32 v192, v127, v211
	v_fmac_f32_e32 v144, v106, v179
	v_fmac_f32_e32 v193, v104, v192
	v_fmac_f32_e32 v145, v104, v144
	v_fmac_f32_e32 v193, v127, v144
	v_fmac_f32_e32 v145, v106, v192
	v_fmac_f32_e32 v194, v104, v193
	v_fmac_f32_e32 v146, v104, v145
	v_fmac_f32_e32 v194, v127, v145
	v_fmac_f32_e32 v146, v106, v193
	v_fmac_f32_e32 v195, v104, v194
	v_fmac_f32_e32 v147, v104, v146
	v_fmac_f32_e32 v195, v127, v146
	v_fmac_f32_e32 v147, v106, v194
	v_fmac_f32_e32 v180, v104, v195
	v_fmac_f32_e32 v212, v104, v147
	v_fmac_f32_e32 v180, v127, v147
	v_fmac_f32_e32 v212, v106, v195
	v_fmac_f32_e32 v181, v104, v180
	v_fmac_f32_e32 v213, v104, v212
	v_fmac_f32_e32 v181, v127, v212
	v_fmac_f32_e32 v213, v106, v180
	v_fmac_f32_e32 v182, v104, v181
	v_fmac_f32_e32 v214, v104, v213
	v_fmac_f32_e32 v182, v127, v213
	v_fmac_f32_e32 v214, v106, v181
	v_fmac_f32_e32 v183, v104, v182
	v_fmac_f32_e32 v215, v104, v214
	v_fmac_f32_e32 v183, v127, v214
	v_fmac_f32_e32 v215, v106, v182
	v_fmac_f32_e32 v196, v104, v183
	v_fmac_f32_e32 v148, v104, v215
	v_fmac_f32_e32 v196, v127, v215
	v_fmac_f32_e32 v148, v106, v183
	v_fmac_f32_e32 v197, v104, v196
	v_fmac_f32_e32 v149, v104, v148
	v_fmac_f32_e32 v197, v127, v148
	v_fmac_f32_e32 v149, v106, v196
	v_fmac_f32_e32 v198, v104, v197
	v_fmac_f32_e32 v150, v104, v149
	v_fmac_f32_e32 v198, v127, v149
	v_fmac_f32_e32 v150, v106, v197
	v_fmac_f32_e32 v199, v104, v198
	v_fmac_f32_e32 v151, v104, v150
	v_fmac_f32_e32 v199, v127, v150
	v_fmac_f32_e32 v151, v106, v198
	v_fmac_f32_e32 v184, v104, v199
	v_fmac_f32_e32 v216, v104, v151
	v_fmac_f32_e32 v184, v127, v151
	v_fmac_f32_e32 v216, v106, v199
	v_fmac_f32_e32 v185, v104, v184
	v_fmac_f32_e32 v217, v104, v216
	v_fmac_f32_e32 v185, v127, v216
	v_fmac_f32_e32 v217, v106, v184
	v_fmac_f32_e32 v186, v104, v185
	v_fmac_f32_e32 v218, v104, v217
	v_fmac_f32_e32 v186, v127, v217
	v_fmac_f32_e32 v218, v106, v185
	v_fmac_f32_e32 v187, v104, v186
	v_fmac_f32_e32 v219, v104, v218
	v_fmac_f32_e32 v187, v127, v218
	v_fmac_f32_e32 v219, v106, v186
	v_fmac_f32_e32 v200, v104, v187
	v_fmac_f32_e32 v152, v104, v219
	v_fmac_f32_e32 v200, v127, v219
	v_fmac_f32_e32 v152, v106, v187
	v_fmac_f32_e32 v201, v104, v200
	v_fmac_f32_e32 v153, v104, v152
	v_fmac_f32_e32 v201, v127, v152
	v_fmac_f32_e32 v153, v106, v200
	v_fmac_f32_e32 v202, v104, v201
	v_fmac_f32_e32 v154, v104, v153
	v_fmac_f32_e32 v202, v127, v153
	v_fmac_f32_e32 v154, v106, v201
	v_fmac_f32_e32 v203, v104, v202
	v_fmac_f32_e32 v155, v104, v154
	v_fmac_f32_e32 v203, v127, v154
	v_fmac_f32_e32 v155, v106, v202
	v_fmac_f32_e32 v188, v104, v203
	v_fmac_f32_e32 v220, v104, v155
	v_fmac_f32_e32 v188, v127, v155
	v_fmac_f32_e32 v220, v106, v203
	v_fmac_f32_e32 v189, v104, v188
	v_fmac_f32_e32 v221, v104, v220
	v_fmac_f32_e32 v189, v127, v220
	v_fmac_f32_e32 v221, v106, v188
	v_fmac_f32_e32 v190, v104, v189
	v_fmac_f32_e32 v222, v104, v221
	v_fmac_f32_e32 v190, v127, v221
	v_fmac_f32_e32 v222, v106, v189
	v_fmac_f32_e32 v191, v104, v190
	v_fmac_f32_e32 v223, v104, v222
	v_fmac_f32_e32 v191, v127, v222
	v_fmac_f32_e32 v223, v106, v190
	v_fmac_f32_e32 v204, v104, v191
	v_fmac_f32_e32 v156, v104, v223
	v_fmac_f32_e32 v204, v127, v223
	v_fmac_f32_e32 v156, v106, v191
	v_fmac_f32_e32 v205, v104, v204
	v_fmac_f32_e32 v157, v104, v156
	v_fmac_f32_e32 v205, v127, v156
	v_fmac_f32_e32 v157, v106, v204
	v_fmac_f32_e32 v206, v104, v205
	v_fmac_f32_e32 v158, v104, v157
	v_fmac_f32_e32 v206, v127, v157
	v_fmac_f32_e32 v158, v106, v205
	v_fmac_f32_e32 v207, v104, v206
	v_fmac_f32_e32 v159, v104, v158
	v_fmac_f32_e32 v207, v127, v158
	v_fmac_f32_e32 v159, v106, v206
	v_mov_b32_e32 v6, v207
	v_mov_b32_e32 v7, v159
	s_waitcnt lgkmcnt(0)
	s_load_dwordx2 s[4:5], s[0:1], 0x150
	v_ashrrev_i32_e32 v103, 31, v102
	v_lshlrev_b64 v[0:1], 9, v[102:103]
	v_mov_b32_e32 v97, v169
	s_waitcnt lgkmcnt(0)
	v_lshl_add_u64 v[0:1], s[4:5], 0, v[0:1]
	v_lshl_add_u64 v[0:1], v[0:1], 0, v[96:97]
	v_add_co_u32_e32 v0, vcc, 0x2d381000, v0
	s_mov_b64 s[4:5], 0
	s_nop 0
	v_addc_co_u32_e32 v1, vcc, 0, v1, vcc
	global_store_dwordx2 v[0:1], v[6:7], off offset:2048
